# static shares for the P1 work items and the gMLP chunks (no atomic tickets) on top of p1loop+p1nt+tailnt+gmlpnt
# baseline (speedup 1.0000x reference)
.LBB0_81:
	v_and_b32_e32 v9, 15, v0
	v_lshlrev_b32_e32 v1, 1, v9
	v_cvt_f32_ubyte0_e32 v1, v1
	v_mul_f32_e32 v1, 0xbd000000, v1
	v_mov_b32_e32 v2, 0x461c4000
	v_cmp_eq_f32_e32 vcc, 0, v1
	s_mov_b32 s2, 0x3f2aaaab
	s_mov_b32 s7, 0x42b17218
	v_cndmask_b32_e64 v2, v2, 1.0, vcc
	v_frexp_mant_f32_e32 v4, v2
	v_cmp_gt_f32_e64 s[4:5], s2, v4
	s_mov_b32 s2, 0x3f317218
	s_mov_b32 s6, 0x7f800000
	v_cndmask_b32_e64 v5, 1.0, 2.0, s[4:5]
	v_mul_f32_e32 v4, v4, v5
	v_add_f32_e32 v7, 1.0, v4
	v_rcp_f32_e32 v8, v7
	v_add_f32_e32 v5, -1.0, v7
	v_sub_f32_e32 v11, v4, v5
	v_add_f32_e32 v5, -1.0, v4
	v_mul_f32_e32 v14, v5, v8
	v_mul_f32_e32 v6, v7, v14
	v_fma_f32 v10, v14, v7, -v6
	v_fmac_f32_e32 v10, v14, v11
	v_add_f32_e32 v4, v6, v10
	v_sub_f32_e32 v7, v5, v4
	v_pk_add_f32 v[12:13], v[4:5], v[6:7] neg_lo:[0,1] neg_hi:[0,1]
	v_mov_b32_e32 v11, v4
	v_pk_add_f32 v[4:5], v[12:13], v[10:11] neg_lo:[0,1] neg_hi:[0,1]
	v_mov_b32_e32 v10, 0x3e91f4c4
	v_add_f32_e32 v4, v4, v5
	v_add_f32_e32 v4, v7, v4
	v_mul_f32_e32 v5, v8, v4
	v_add_f32_e32 v4, v14, v5
	v_sub_f32_e32 v6, v4, v14
	v_sub_f32_e32 v8, v5, v6
	v_mul_f32_e32 v5, v4, v4
	v_fma_f32 v7, v4, v4, -v5
	v_add_f32_e32 v6, v8, v8
	v_fmac_f32_e32 v7, v4, v6
	v_add_f32_e32 v6, v5, v7
	v_fmac_f32_e32 v10, 0x3e76c4e1, v6
	v_fmaak_f32 v10, v6, v10, 0x3ecccdef
	v_sub_f32_e32 v5, v6, v5
	v_sub_f32_e32 v16, v7, v5
	v_mul_f32_e32 v5, v6, v10
	v_fma_f32 v7, v6, v10, -v5
	v_fmac_f32_e32 v7, v16, v10
	v_add_f32_e32 v10, v5, v7
	v_add_f32_e32 v11, 0x3f2aaaaa, v10
	v_sub_f32_e32 v5, v10, v5
	v_sub_f32_e32 v5, v7, v5
	v_add_f32_e32 v7, 0xbf2aaaaa, v11
	v_add_f32_e32 v5, 0x31739010, v5
	v_sub_f32_e32 v7, v10, v7
	v_pk_mul_f32 v[12:13], v[4:5], v[6:7]
	v_pk_add_f32 v[14:15], v[4:5], v[6:7]
	v_fma_f32 v10, v6, v4, -v12
	v_fmac_f32_e32 v10, v6, v8
	v_mov_b32_e32 v13, v15
	v_fmac_f32_e32 v10, v16, v4
	v_pk_add_f32 v[6:7], v[12:13], v[10:11]
	v_readlane_b32 s46, v253, 32
	v_sub_f32_e32 v5, v6, v12
	v_sub_f32_e32 v5, v10, v5
	v_sub_f32_e32 v10, v11, v7
	v_add_f32_e32 v13, v15, v10
	v_cvt_f64_f32_e32 v[14:15], v2
	v_frexp_exp_i32_f64_e32 v2, v[14:15]
	v_subbrev_co_u32_e64 v2, s[4:5], 0, v2, s[4:5]
	v_cvt_f32_i32_e32 v2, v2
	v_pk_mul_f32 v[10:11], v[6:7], v[6:7] op_sel:[0,1] op_sel_hi:[1,0]
	v_ldexp_f32 v15, v4, 1
	v_fma_f32 v12, v6, v7, -v10
	v_fmac_f32_e32 v12, v6, v13
	v_mul_f32_e32 v6, 0x3f317218, v2
	v_fmac_f32_e32 v12, v5, v7
	v_fma_f32 v5, v2, s2, -v6
	v_fmamk_f32 v14, v2, 0xb102e308, v5
	v_add_f32_e32 v7, v10, v12
	v_pk_add_f32 v[4:5], v[6:7], v[14:15]
	v_mov_b32_e32 v16, v7
	v_mov_b32_e32 v17, v5
	v_mov_b32_e32 v11, v15
	v_pk_add_f32 v[10:11], v[16:17], v[10:11] neg_lo:[0,1] neg_hi:[0,1]
	v_mov_b32_e32 v13, v7
	v_ldexp_f32 v2, v8, 1
	v_pk_add_f32 v[10:11], v[12:13], v[10:11] neg_lo:[0,1] neg_hi:[0,1]
	v_mov_b32_e32 v15, v4
	v_add_f32_e32 v2, v2, v10
	v_add_f32_e32 v7, v2, v11
	v_pk_add_f32 v[10:11], v[4:5], v[6:7] neg_lo:[0,1] neg_hi:[0,1]
	v_pk_add_f32 v[12:13], v[4:5], v[6:7]
	v_mov_b32_e32 v6, v7
	v_mov_b32_e32 v11, v13
	v_pk_add_f32 v[16:17], v[14:15], v[10:11] neg_lo:[0,1] neg_hi:[0,1]
	v_pk_add_f32 v[10:11], v[14:15], v[10:11]
	v_mov_b32_e32 v7, v4
	v_pk_add_f32 v[14:15], v[10:11], v[4:5] op_sel:[1,0] op_sel_hi:[0,1] neg_lo:[0,1] neg_hi:[0,1]
	v_pk_add_f32 v[18:19], v[12:13], v[14:15] op_sel_hi:[1,0] neg_lo:[0,1] neg_hi:[0,1]
	v_mov_b32_e32 v12, v13
	v_mov_b32_e32 v13, v11
	v_pk_mov_b32 v[14:15], v[4:5], v[14:15] op_sel:[1,0]
	v_mov_b32_e32 v18, v16
	v_pk_add_f32 v[12:13], v[12:13], v[14:15] neg_lo:[0,1] neg_hi:[0,1]
	v_mov_b32_e32 v17, v11
	v_pk_add_f32 v[4:5], v[6:7], v[12:13] neg_lo:[0,1] neg_hi:[0,1]
	s_movk_i32 s2, 0x204
	v_pk_add_f32 v[6:7], v[18:19], v[4:5]
	s_lshl_b32 s0, s46, 14
	v_pk_add_f32 v[12:13], v[6:7], v[6:7] op_sel:[0,1] op_sel_hi:[1,0]
	s_add_i32 s3, s0, 0
	v_pk_add_f32 v[10:11], v[10:11], v[12:13] op_sel:[1,0] op_sel_hi:[0,1]
	v_mov_b32_e32 v7, v10
	v_pk_add_f32 v[14:15], v[6:7], v[16:17] neg_lo:[0,1] neg_hi:[0,1]
	v_mov_b32_e32 v5, v12
	v_sub_f32_e32 v2, v6, v14
	v_pk_add_f32 v[4:5], v[4:5], v[14:15] neg_lo:[0,1] neg_hi:[0,1]
	v_sub_f32_e32 v2, v16, v2
	v_add_f32_e32 v2, v4, v2
	v_add_f32_e32 v2, v2, v5
	v_add_f32_e32 v4, v10, v2
	v_sub_f32_e32 v5, v4, v10
	v_sub_f32_e32 v2, v2, v5
	v_mul_f32_e32 v5, v1, v4
	v_fma_f32 v4, v1, v4, -v5
	v_fmac_f32_e32 v4, v1, v2
	v_add_f32_e32 v2, v5, v4
	v_cmp_class_f32_e64 s[4:5], v5, s2
	v_sub_f32_e32 v6, v2, v5
	v_sub_f32_e32 v4, v4, v6
	v_cndmask_b32_e64 v2, v2, v5, s[4:5]
	v_mov_b32_e32 v5, 0x37000000
	v_cmp_eq_f32_e64 s[4:5], s7, v2
	v_lshrrev_b32_e32 v18, 3, v218
	s_mov_b64 s[86:87], s[58:59]
	v_cndmask_b32_e64 v5, 0, v5, s[4:5]
	v_sub_f32_e32 v6, v2, v5
	s_mov_b32 s4, 0x3fb8aa3b
	v_mul_f32_e32 v7, 0x3fb8aa3b, v6
	v_fma_f32 v8, v6, s4, -v7
	v_rndne_f32_e32 v10, v7
	v_fmamk_f32 v8, v6, 0x32a5705f, v8
	v_sub_f32_e32 v7, v7, v10
	v_add_f32_e32 v7, v7, v8
	v_exp_f32_e32 v7, v7
	v_cvt_i32_f32_e32 v8, v10
	v_cmp_neq_f32_e64 s[4:5], |v2|, s6
	v_cmp_eq_u32_e64 s[0:1], 0, v0
	v_or_b32_e32 v3, 0xfffde000, v218
	v_cndmask_b32_e64 v2, 0, v4, s[4:5]
	s_mov_b32 s4, 0xc2ce8ed0
	v_ldexp_f32 v4, v7, v8
	v_cmp_ngt_f32_e64 s[4:5], s4, v6
	v_add_f32_e32 v2, v5, v2
	v_mov_b32_e32 v5, 0x7f800000
	v_cndmask_b32_e64 v4, 0, v4, s[4:5]
	v_cmp_nlt_f32_e64 s[4:5], s7, v6
	v_or_b32_e32 v20, 8, v18
	v_or_b32_e32 v21, 16, v18
	v_cndmask_b32_e64 v4, v5, v4, s[4:5]
	v_fma_f32 v2, v4, v2, v4
	v_cmp_class_f32_e64 s[4:5], v4, s2
	v_or_b32_e32 v22, 24, v18
	s_movk_i32 s16, 0x89f
	v_cndmask_b32_e64 v2, v2, v4, s[4:5]
	v_cmp_neq_f32_e64 s[4:5], v1, |v1|
	s_brev_b32 s17, 18
	s_mov_b32 s18, 0xfe5163ab
	v_cndmask_b32_e64 v4, v5, 0, s[4:5]
	v_cmp_class_f32_e64 s[4:5], v1, s2
	v_mov_b32_e32 v1, 0xfff10000
	v_cndmask_b32_e64 v4, v4, 1.0, vcc
	v_lshl_or_b32 v17, v218, 3, v1
	v_and_b32_e32 v1, 31, v0
	v_cndmask_b32_e64 v16, |v2|, v4, s[4:5]
	v_lshlrev_b32_e32 v4, 2, v1
	v_mov_b32_e32 v5, 0
	v_lshlrev_b32_e32 v1, 3, v0
	s_waitcnt lgkmcnt(0)
	v_lshl_add_u64 v[6:7], s[60:61], 0, v[4:5]
	v_add_u32_e32 v8, s3, v4
	v_and_b32_e32 v4, 56, v1
	v_readlane_b32 s4, v253, 23
	v_lshlrev_b32_e32 v10, 1, v4
	v_mov_b32_e32 v11, v5
	v_readlane_b32 s5, v253, 24
	v_lshrrev_b32_e32 v2, 5, v218
	v_mul_u32_u24_e32 v1, 0x84, v4
	v_lshl_add_u64 v[10:11], s[4:5], 0, v[10:11]
	v_lshl_add_u64 v[12:13], s[44:45], 0, v[4:5]
	s_mov_b64 s[4:5], 0xe00000
	v_lshlrev_b32_e32 v4, 2, v18
	s_movk_i32 s2, 0x84
	v_lshl_add_u64 v[12:13], v[12:13], 0, s[4:5]
	v_add3_u32 v19, s3, v1, v4
	v_mov_b32_e32 v1, v2
	s_add_i32 s3, 0, 0x20184
	s_mov_b32 s19, 0x3c439041
	s_mov_b32 s20, 0xdb629599
	s_mov_b32 s21, 0xf534ddc0
	s_mov_b32 s22, 0xfc2757d1
	s_mov_b32 s23, 0x4e441529
	s_mov_b32 s24, 0xa2f9836e
	s_mov_b32 s25, 0x3fc90fda
	s_mov_b32 s26, 0x3f22f983
	s_mov_b32 s27, 0xbfc90fda
	v_mov_b32_e32 v23, 0x3c0881c4
	v_mov_b32_e32 v24, 0xbab64f3b
	s_brev_b32 s28, 1
	s_movk_i32 s29, 0x1f8
	s_movk_i32 s30, 0x7fff
	s_mov_b32 s31, 0xffff0000
	s_movk_i32 s33, 0xf500
	s_movk_i32 s34, 0x3c00
	v_not_b32_e32 v25, 63
	v_not_b32_e32 v26, 31
	v_mov_b32_e32 v27, 0x7fc00000
	s_mov_b64 s[84:85], s[56:57]
	s_mov_b64 s[82:83], s[54:55]
	s_mov_b64 s[80:81], s[52:53]
	v_readlane_b32 s54, v253, 20
	v_readlane_b32 s47, v253, 33
	s_lshl_b32 s35, s54, 3
	v_mov_b32_e32 v250, s35
	s_add_i32 s35, s35, 0x400
	s_cmp_lt_u32 s54, 0x80
	s_cselect_b32 s35, 0x1000, s35
	s_cmp_gt_u32 s54, 0x93
	s_cselect_b32 s35, 0x1000, s35
	v_mov_b32_e32 v251, s35
	s_branch .LBB0_84

.LBB0_84:
	s_barrier
	v_readfirstlane_b32 s35, v250
	v_mov_b32_e32 v250, v251
	v_mov_b32_e32 v251, 0x1000
	s_mov_b64 s[4:5], -1
	s_nop 0
	s_cmp_gt_i32 s35, s16
	s_cbranch_scc1 .LBB0_83
	s_add_i32 s35, s35, s46
	s_cmpk_gt_i32 s35, 0x89f
	s_cbranch_scc1 .LBB0_82
	s_cmpk_gt_i32 s35, 0x77f
	s_cbranch_scc0 .LBB0_103
	s_cmpk_gt_u32 s35, 0x87f
	s_cbranch_scc0 .LBB0_101
	v_lshl_add_u32 v4, s35, 6, v3
	v_lshrrev_b32_e32 v14, 4, v4
	v_cvt_f32_u32_e32 v4, v14
	v_mul_f32_e32 v28, v16, v4
	v_and_b32_e32 v29, 0x7fffffff, v28
	v_lshrrev_b32_e32 v4, 23, v29
	v_and_b32_e32 v15, 0x7fffff, v29
	v_cmp_nlt_f32_e64 s[10:11], |v28|, s17
	v_add_u32_e32 v31, 0xffffff88, v4
	v_or_b32_e32 v30, 0x800000, v15
	s_and_saveexec_b64 s[4:5], s[10:11]
	s_xor_b64 s[14:15], exec, s[4:5]
	s_cbranch_execz .LBB0_94
	v_cmp_lt_u32_e32 vcc, 63, v31
	v_mad_u64_u32 v[32:33], s[8:9], v30, s18, 0
	s_nop 0
	v_cndmask_b32_e32 v4, 0, v25, vcc
	v_add_u32_e32 v4, v4, v31
	v_cmp_lt_u32_e64 s[4:5], 31, v4
	s_nop 1
	v_cndmask_b32_e64 v15, 0, v26, s[4:5]
	v_add_u32_e32 v4, v15, v4
	v_cmp_lt_u32_e64 s[6:7], 31, v4
	s_nop 1
	v_cndmask_b32_e64 v15, 0, v26, s[6:7]
	v_add_u32_e32 v15, v15, v4
	v_mov_b32_e32 v4, v33
	v_mad_u64_u32 v[34:35], s[8:9], v30, s19, v[4:5]
	v_mov_b32_e32 v4, v35
	v_mad_u64_u32 v[36:37], s[8:9], v30, s20, v[4:5]
	v_mov_b32_e32 v4, v37
	v_mad_u64_u32 v[38:39], s[8:9], v30, s21, v[4:5]
	v_mov_b32_e32 v4, v39
	v_mad_u64_u32 v[40:41], s[8:9], v30, s22, v[4:5]
	v_mov_b32_e32 v4, v41
	v_mad_u64_u32 v[42:43], s[8:9], v30, s23, v[4:5]
	v_mov_b32_e32 v4, v43
	v_mad_u64_u32 v[44:45], s[8:9], v30, s24, v[4:5]
	v_cndmask_b32_e32 v33, v42, v38, vcc
	v_cndmask_b32_e32 v4, v44, v40, vcc
	v_cndmask_b32_e32 v37, v45, v42, vcc
	v_cndmask_b32_e64 v35, v4, v33, s[4:5]
	v_cndmask_b32_e64 v4, v37, v4, s[4:5]
	v_cndmask_b32_e32 v37, v40, v36, vcc
	v_cndmask_b32_e64 v33, v33, v37, s[4:5]
	v_sub_u32_e32 v39, 32, v15
	v_cmp_eq_u32_e64 s[8:9], 0, v15
	v_cndmask_b32_e32 v15, v38, v34, vcc
	v_cndmask_b32_e64 v4, v4, v35, s[6:7]
	v_cndmask_b32_e64 v35, v35, v33, s[6:7]
	v_cndmask_b32_e64 v34, v37, v15, s[4:5]
	v_alignbit_b32 v40, v4, v35, v39
	v_cndmask_b32_e64 v33, v33, v34, s[6:7]
	v_cndmask_b32_e64 v4, v40, v4, s[8:9]
	v_alignbit_b32 v37, v35, v33, v39
	v_cndmask_b32_e32 v32, v36, v32, vcc
	v_cndmask_b32_e64 v35, v37, v35, s[8:9]
	v_bfe_u32 v40, v4, 29, 1
	v_cndmask_b32_e64 v15, v15, v32, s[4:5]
	v_alignbit_b32 v37, v4, v35, 30
	v_sub_u32_e32 v41, 0, v40
	v_cndmask_b32_e64 v15, v34, v15, s[6:7]
	v_xor_b32_e32 v37, v37, v41
	v_alignbit_b32 v32, v33, v15, v39
	v_cndmask_b32_e64 v32, v32, v33, s[8:9]
	v_ffbh_u32_e32 v34, v37
	v_alignbit_b32 v33, v35, v32, 30
	v_min_u32_e32 v34, 32, v34
	v_alignbit_b32 v15, v32, v15, 30
	v_xor_b32_e32 v33, v33, v41
	v_sub_u32_e32 v35, 31, v34
	v_xor_b32_e32 v15, v15, v41
	v_alignbit_b32 v36, v37, v33, v35
	v_alignbit_b32 v15, v33, v15, v35
	v_alignbit_b32 v32, v36, v15, 9
	v_ffbh_u32_e32 v33, v32
	v_min_u32_e32 v33, 32, v33
	v_lshrrev_b32_e32 v38, 29, v4
	v_not_b32_e32 v35, v33
	v_alignbit_b32 v15, v32, v15, v35
	v_lshlrev_b32_e32 v32, 31, v38
	v_or_b32_e32 v35, 0x33000000, v32
	v_add_lshl_u32 v33, v33, v34, 23
	v_lshrrev_b32_e32 v15, 9, v15
	v_sub_u32_e32 v33, v35, v33
	v_or_b32_e32 v32, 0.5, v32
	v_lshlrev_b32_e32 v34, 23, v34
	v_or_b32_e32 v15, v33, v15
	v_lshrrev_b32_e32 v33, 9, v36
	v_sub_u32_e32 v32, v32, v34
	v_or_b32_e32 v32, v33, v32
	v_mul_f32_e32 v33, 0x3fc90fda, v32
	v_fma_f32 v34, v32, s25, -v33
	v_fmac_f32_e32 v34, 0x33a22168, v32
	v_fmac_f32_e32 v34, 0x3fc90fda, v15
	v_lshrrev_b32_e32 v4, 30, v4
	v_add_f32_e32 v15, v33, v34
	v_add_u32_e32 v4, v40, v4

.LBB0_866:
	s_waitcnt vmcnt(63) expcnt(7) lgkmcnt(15)
	s_barrier
	v_readlane_b32 s10, v253, 20
	s_mov_b64 s[6:7], -1
	s_nop 1
	s_lshl_b32 s6, s10, 7
	s_ashr_i32 s7, s6, 31
	s_lshl_b64 s[6:7], s[6:7], 10
	v_lshl_add_u64 v[58:59], v[132:133], 0, s[6:7]
	s_waitcnt vmcnt(0)
	v_add_co_u32_e32 v10, vcc, 0x2000, v58
	s_ashr_i32 s11, s10, 31
	s_nop 0
	v_addc_co_u32_e32 v11, vcc, 0, v59, vcc
	global_load_dwordx4 v[2:5], v[58:59], off nt
	global_load_dwordx4 v[6:9], v[10:11], off nt
	v_add_co_u32_e32 v10, vcc, 0x4000, v58
	s_lshl_b64 s[6:7], s[10:11], 16
	s_nop 0
	v_addc_co_u32_e32 v11, vcc, 0, v59, vcc
	v_add_co_u32_e32 v14, vcc, 0x6000, v58
	s_lshl_b64 s[8:9], s[10:11], 17
	s_nop 0
	v_addc_co_u32_e32 v15, vcc, 0, v59, vcc
	v_add_co_u32_e32 v18, vcc, 0x8000, v58
	global_load_dwordx4 v[10:13], v[10:11], off nt
	s_nop 0
	global_load_dwordx4 v[14:17], v[14:15], off nt
	v_addc_co_u32_e32 v19, vcc, 0, v59, vcc
	v_add_co_u32_e32 v22, vcc, 0xa000, v58
	s_lshl_b64 s[10:11], s[10:11], 18
	s_nop 0
	v_addc_co_u32_e32 v23, vcc, 0, v59, vcc
	v_add_co_u32_e32 v26, vcc, 0xc000, v58
	global_load_dwordx4 v[18:21], v[18:19], off nt
	s_nop 0
	global_load_dwordx4 v[22:25], v[22:23], off nt
	v_addc_co_u32_e32 v27, vcc, 0, v59, vcc
	v_add_co_u32_e32 v30, vcc, 0xe000, v58
	s_mov_b32 s14, 0
	s_nop 0
	v_addc_co_u32_e32 v31, vcc, 0, v59, vcc
	v_add_co_u32_e32 v34, vcc, 0x10000, v58
	global_load_dwordx4 v[26:29], v[26:27], off nt
	s_nop 0
	global_load_dwordx4 v[30:33], v[30:31], off nt
	v_addc_co_u32_e32 v35, vcc, 0, v59, vcc
	v_add_co_u32_e32 v38, vcc, 0x12000, v58
	v_lshl_add_u64 v[148:149], v[146:147], 0, s[10:11]
	s_nop 0
	v_addc_co_u32_e32 v39, vcc, 0, v59, vcc
	v_add_co_u32_e32 v42, vcc, 0x14000, v58
	global_load_dwordx4 v[34:37], v[34:35], off nt
	s_nop 0
	global_load_dwordx4 v[38:41], v[38:39], off nt
	v_addc_co_u32_e32 v43, vcc, 0, v59, vcc
	v_add_co_u32_e32 v46, vcc, 0x16000, v58
	s_mov_b64 s[10:11], -1
	s_nop 0
	v_addc_co_u32_e32 v47, vcc, 0, v59, vcc
	v_add_co_u32_e32 v50, vcc, 0x18000, v58
	global_load_dwordx4 v[42:45], v[42:43], off nt
	s_nop 0
	global_load_dwordx4 v[46:49], v[46:47], off nt
	v_addc_co_u32_e32 v51, vcc, 0, v59, vcc
	v_add_co_u32_e32 v54, vcc, 0x1a000, v58
	s_nop 1
	v_addc_co_u32_e32 v55, vcc, 0, v59, vcc
	v_add_co_u32_e32 v60, vcc, 0x1c000, v58
	global_load_dwordx4 v[50:53], v[50:51], off nt
	s_nop 0
	global_load_dwordx4 v[54:57], v[54:55], off nt
	v_addc_co_u32_e32 v61, vcc, 0, v59, vcc
	v_add_co_u32_e32 v62, vcc, 0x1e000, v58
	s_nop 1
	v_addc_co_u32_e32 v63, vcc, 0, v59, vcc
	global_load_dwordx4 v[58:61], v[60:61], off nt
	s_nop 0
	global_load_dwordx4 v[62:65], v[62:63], off nt
	s_waitcnt vmcnt(15)
	ds_write_b16 v135, v2
	ds_write_b16_d16_hi v135, v2 offset:272
	ds_write_b16 v135, v3 offset:544
	ds_write_b16_d16_hi v135, v3 offset:816
	ds_write_b16 v135, v4 offset:1088
	ds_write_b16_d16_hi v135, v4 offset:1360
	ds_write_b16 v135, v5 offset:1632
	ds_write_b16_d16_hi v135, v5 offset:1904
	s_waitcnt vmcnt(14)
	ds_write_b16 v135, v6 offset:16
	ds_write_b16_d16_hi v135, v6 offset:256
	ds_write_b16 v135, v7 offset:560
	ds_write_b16_d16_hi v135, v7 offset:800
	ds_write_b16 v135, v8 offset:1104
	ds_write_b16_d16_hi v135, v8 offset:1344
	ds_write_b16 v135, v9 offset:1648
	ds_write_b16_d16_hi v135, v9 offset:1888
	s_waitcnt vmcnt(13)
	ds_write_b16 v135, v10 offset:32
	ds_write_b16_d16_hi v135, v10 offset:304
	ds_write_b16 v135, v11 offset:512
	ds_write_b16_d16_hi v135, v11 offset:784
	ds_write_b16 v135, v12 offset:1120
	ds_write_b16_d16_hi v135, v12 offset:1392
	ds_write_b16 v135, v13 offset:1600
	ds_write_b16_d16_hi v135, v13 offset:1872
	s_waitcnt vmcnt(12)
	ds_write_b16 v135, v14 offset:48
	ds_write_b16_d16_hi v135, v14 offset:288
	ds_write_b16 v135, v15 offset:528
	ds_write_b16_d16_hi v135, v15 offset:768
	ds_write_b16 v135, v16 offset:1136
	ds_write_b16_d16_hi v135, v16 offset:1376
	ds_write_b16 v135, v17 offset:1616
	ds_write_b16_d16_hi v135, v17 offset:1856
	s_waitcnt vmcnt(11)
	ds_write_b16 v135, v18 offset:64
	ds_write_b16_d16_hi v135, v18 offset:336
	ds_write_b16 v135, v19 offset:608
	ds_write_b16_d16_hi v135, v19 offset:880
	ds_write_b16 v135, v20 offset:1024
	ds_write_b16_d16_hi v135, v20 offset:1296
	ds_write_b16 v135, v21 offset:1568
	ds_write_b16_d16_hi v135, v21 offset:1840
	s_waitcnt vmcnt(10)
	ds_write_b16 v135, v22 offset:80
	ds_write_b16_d16_hi v135, v22 offset:320
	ds_write_b16 v135, v23 offset:624
	ds_write_b16_d16_hi v135, v23 offset:864
	ds_write_b16 v135, v24 offset:1040
	ds_write_b16_d16_hi v135, v24 offset:1280
	ds_write_b16 v135, v25 offset:1584
	ds_write_b16_d16_hi v135, v25 offset:1824
	s_waitcnt vmcnt(9)
	ds_write_b16 v135, v26 offset:96
	ds_write_b16_d16_hi v135, v26 offset:368
	ds_write_b16 v135, v27 offset:576
	ds_write_b16_d16_hi v135, v27 offset:848
	ds_write_b16 v135, v28 offset:1056
	ds_write_b16_d16_hi v135, v28 offset:1328
	ds_write_b16 v135, v29 offset:1536
	ds_write_b16_d16_hi v135, v29 offset:1808
	s_waitcnt vmcnt(8)
	ds_write_b16 v135, v30 offset:112
	ds_write_b16_d16_hi v135, v30 offset:352
	ds_write_b16 v135, v31 offset:592
	ds_write_b16_d16_hi v135, v31 offset:832
	ds_write_b16 v135, v32 offset:1072
	ds_write_b16_d16_hi v135, v32 offset:1312
	ds_write_b16 v135, v33 offset:1552
	ds_write_b16_d16_hi v135, v33 offset:1792
	s_waitcnt vmcnt(7)
	ds_write_b16 v162, v34 offset:128
	ds_write_b16_d16_hi v162, v34 offset:400
	ds_write_b16 v162, v35 offset:672
	ds_write_b16_d16_hi v162, v35 offset:944
	ds_write_b16 v162, v36 offset:1216
	ds_write_b16_d16_hi v162, v36 offset:1488
	ds_write_b16 v162, v37 offset:1760
	ds_write_b16_d16_hi v162, v37 offset:2032
	s_waitcnt vmcnt(6)
	ds_write_b16 v162, v38 offset:144
	ds_write_b16_d16_hi v162, v38 offset:384
	ds_write_b16 v162, v39 offset:688
	ds_write_b16_d16_hi v162, v39 offset:928
	ds_write_b16 v162, v40 offset:1232
	ds_write_b16_d16_hi v162, v40 offset:1472
	ds_write_b16 v162, v41 offset:1776
	ds_write_b16_d16_hi v162, v41 offset:2016
	s_waitcnt vmcnt(5)
	ds_write_b16 v162, v42 offset:160
	ds_write_b16_d16_hi v162, v42 offset:432
	ds_write_b16 v162, v43 offset:640
	ds_write_b16_d16_hi v162, v43 offset:912
	ds_write_b16 v162, v44 offset:1248
	ds_write_b16_d16_hi v162, v44 offset:1520
	ds_write_b16 v162, v45 offset:1728
	ds_write_b16_d16_hi v162, v45 offset:2000
	s_waitcnt vmcnt(4)
	ds_write_b16 v162, v46 offset:176
	ds_write_b16_d16_hi v162, v46 offset:416
	ds_write_b16 v162, v47 offset:656
	ds_write_b16_d16_hi v162, v47 offset:896
	ds_write_b16 v162, v48 offset:1264
	ds_write_b16_d16_hi v162, v48 offset:1504
	ds_write_b16 v162, v49 offset:1744
	ds_write_b16_d16_hi v162, v49 offset:1984
	s_waitcnt vmcnt(3)
	ds_write_b16 v162, v50 offset:192
	ds_write_b16_d16_hi v162, v50 offset:464
	ds_write_b16 v162, v51 offset:736
	ds_write_b16_d16_hi v162, v51 offset:1008
	ds_write_b16 v162, v52 offset:1152
	ds_write_b16_d16_hi v162, v52 offset:1424
	ds_write_b16 v162, v53 offset:1696
	ds_write_b16_d16_hi v162, v53 offset:1968
	s_waitcnt vmcnt(2)
	ds_write_b16 v162, v54 offset:208
	ds_write_b16_d16_hi v162, v54 offset:448
	ds_write_b16 v162, v55 offset:752
	ds_write_b16_d16_hi v162, v55 offset:992
	ds_write_b16 v162, v56 offset:1168
	ds_write_b16_d16_hi v162, v56 offset:1408
	ds_write_b16 v162, v57 offset:1712
	ds_write_b16_d16_hi v162, v57 offset:1952
	s_waitcnt vmcnt(1)
	ds_write_b16 v162, v58 offset:224
	ds_write_b16_d16_hi v162, v58 offset:496
	ds_write_b16 v162, v59 offset:704
	ds_write_b16_d16_hi v162, v59 offset:976
	ds_write_b16 v162, v60 offset:1184
	ds_write_b16_d16_hi v162, v60 offset:1456
	ds_write_b16 v162, v61 offset:1664
	ds_write_b16_d16_hi v162, v61 offset:1936
	s_waitcnt vmcnt(0)
	ds_write_b16 v162, v62 offset:240
	ds_write_b16_d16_hi v162, v62 offset:480
	ds_write_b16 v162, v63 offset:720
	ds_write_b16_d16_hi v162, v63 offset:960
	ds_write_b16 v162, v64 offset:1200
	ds_write_b16_d16_hi v162, v64 offset:1440
	ds_write_b16 v162, v65 offset:1680
	ds_write_b16_d16_hi v162, v65 offset:1920
	s_waitcnt lgkmcnt(0)
	ds_read_b128 v[2:5], v166
	ds_read_b128 v[6:9], v166 offset:4096
	ds_read_b128 v[10:13], v166 offset:8192
	ds_read_b128 v[14:17], v166 offset:12288
	ds_read_b128 v[18:21], v167
	ds_read_b128 v[22:25], v167 offset:4096
	ds_read_b128 v[26:29], v167 offset:8192
	ds_read_b128 v[30:33], v167 offset:12288
	ds_read_b128 v[34:37], v168
	ds_read_b128 v[38:41], v168 offset:4096
	ds_read_b128 v[42:45], v168 offset:8192
	ds_read_b128 v[46:49], v168 offset:12288
	ds_read_b128 v[50:53], v169
	ds_read_b128 v[54:57], v169 offset:4096
	ds_read_b128 v[58:61], v169 offset:8192
	ds_read_b128 v[62:65], v169 offset:12288
.LBB0_872:
	s_lshl_b32 s15, s14, 6
	v_mov_b32_e32 v67, v1
	v_or_b32_e32 v66, s15, v134
	v_lshlrev_b64 v[150:151], 8, v[66:67]
	v_lshl_add_u64 v[152:153], v[136:137], 0, v[150:151]
	global_load_dwordx4 v[70:73], v[152:153], off
	global_load_dwordx4 v[66:69], v[152:153], off offset:64
	v_or_b32_e32 v154, 0x1000, v150
	v_mov_b32_e32 v155, v151
	v_or_b32_e32 v156, 0x2000, v150
	v_mov_b32_e32 v157, v151
	v_or_b32_e32 v150, 0x3000, v150
	v_lshl_add_u64 v[74:75], v[136:137], 0, v[154:155]
	v_lshl_add_u64 v[76:77], v[136:137], 0, v[156:157]
	global_load_dwordx4 v[114:117], v[74:75], off
	global_load_dwordx4 v[118:121], v[76:77], off
	v_or_b32_e32 v176, s15, v163
	v_or_b32_e32 v130, s2, v176
	v_lshl_or_b32 v158, v176, 9, s6
	v_lshl_add_u64 v[204:205], v[130:131], 2, s[70:71]
	v_add_u32_e32 v130, s2, v176
	v_lshl_add_u64 v[184:185], v[140:141], 0, v[156:157]
	global_load_dwordx4 v[184:187], v[184:185], off
	v_mov_b32_e32 v159, s7
	global_load_dwordx4 v[188:191], v[152:153], off offset:128
	v_mov_b32_e32 v201, s7
	v_mov_b32_e32 v203, s7
	v_lshl_add_u64 v[206:207], v[158:159], 1, v[138:139]
	v_or_b32_e32 v200, 0x2000, v158
	v_or_b32_e32 v202, 0x4000, v158
	v_lshl_add_u64 v[220:221], v[142:143], 0, v[156:157]
	v_lshl_add_u64 v[222:223], v[142:143], 0, v[150:151]
	v_lshl_add_u64 v[218:219], v[202:203], 1, v[138:139]
	v_lshl_add_u64 v[224:225], v[144:145], 0, v[150:151]
	v_or_b32_e32 v158, 0x6000, v158
	v_lshl_add_u64 v[158:159], v[158:159], 1, v[138:139]
	v_lshl_or_b32 v171, s14, 16, v164
	v_or_b32_e32 v209, s8, v171
	v_mov_b32_e32 v161, s9
	v_or_b32_e32 v160, 0x4000, v209
	s_and_b64 vcc, exec, s[10:11]
	s_mov_b64 s[10:11], 0
	s_mov_b32 s14, 1
	s_waitcnt vmcnt(5) lgkmcnt(14)
	v_mfma_f32_16x16x32_bf16 v[78:81], v[2:5], v[70:73], 0
	v_mfma_f32_16x16x32_bf16 v[86:89], v[6:9], v[70:73], 0
	s_waitcnt lgkmcnt(13)
	v_mfma_f32_16x16x32_bf16 v[94:97], v[10:13], v[70:73], 0
	s_waitcnt lgkmcnt(12)
	v_mfma_f32_16x16x32_bf16 v[110:113], v[14:17], v[70:73], 0
	v_lshl_add_u64 v[70:71], v[136:137], 0, v[150:151]
	global_load_dwordx4 v[122:125], v[70:71], off
	s_waitcnt vmcnt(5) lgkmcnt(11)
	v_mfma_f32_16x16x32_bf16 v[176:179], v[18:21], v[66:69], v[78:81]
	s_nop 2
	v_lshl_add_u64 v[80:81], v[140:141], 0, v[154:155]
	s_waitcnt lgkmcnt(10)
	v_mfma_f32_16x16x32_bf16 v[86:89], v[22:25], v[66:69], v[86:89]
	global_load_dwordx4 v[180:183], v[80:81], off
	v_lshl_add_u64 v[78:79], v[160:161], 1, v[146:147]
	v_or_b32_e32 v160, 0x8000, v209
	s_waitcnt lgkmcnt(9)
	v_mfma_f32_16x16x32_bf16 v[94:97], v[26:29], v[66:69], v[94:97]
	s_waitcnt lgkmcnt(8)
	v_mfma_f32_16x16x32_bf16 v[110:113], v[30:33], v[66:69], v[110:113]
	v_lshl_add_u64 v[66:67], v[140:141], 0, v[150:151]
	v_lshl_add_u64 v[68:69], v[142:143], 0, v[154:155]
	global_load_dwordx4 v[192:195], v[66:67], off
	global_load_dwordx4 v[196:199], v[68:69], off
	s_waitcnt vmcnt(6)
	v_mfma_f32_16x16x32_bf16 v[82:85], v[6:9], v[118:121], 0
	global_load_dword v208, v[204:205], off
	global_load_dwordx2 v[210:211], v[206:207], off
	global_load_dwordx2 v[212:213], v[206:207], off offset:32
	global_load_dwordx2 v[214:215], v[206:207], off offset:64
	global_load_dwordx2 v[216:217], v[206:207], off offset:96
	v_lshl_add_u64 v[68:69], v[130:131], 2, s[70:71]
	v_mfma_f32_16x16x32_bf16 v[70:73], v[10:13], v[114:117], 0
	v_lshl_add_u64 v[66:67], v[160:161], 1, v[146:147]
	v_or_b32_e32 v160, 0xc000, v209
	v_lshlrev_b32_e32 v130, 1, v171
	v_mfma_f32_16x16x32_bf16 v[106:109], v[2:5], v[114:117], 0
	v_mfma_f32_16x16x32_bf16 v[102:105], v[2:5], v[118:121], 0
	v_mfma_f32_16x16x32_bf16 v[90:93], v[6:9], v[114:117], 0
	v_mfma_f32_16x16x32_bf16 v[126:129], v[10:13], v[118:121], 0
	v_mfma_f32_16x16x32_bf16 v[114:117], v[14:17], v[114:117], 0
	v_mfma_f32_16x16x32_bf16 v[118:121], v[14:17], v[118:121], 0
	s_waitcnt vmcnt(10)
	v_mfma_f32_16x16x32_bf16 v[80:83], v[22:25], v[184:187], v[82:85]
	s_nop 2
	v_lshl_add_u64 v[84:85], v[200:201], 1, v[138:139]
	global_load_dwordx4 v[200:203], v[152:153], off offset:192
	v_mfma_f32_16x16x32_bf16 v[102:105], v[18:21], v[184:187], v[102:105]
	v_mfma_f32_16x16x32_bf16 v[126:129], v[26:29], v[184:187], v[126:129]
	v_mfma_f32_16x16x32_bf16 v[118:121], v[30:33], v[184:187], v[118:121]
	s_waitcnt vmcnt(9)
	v_mfma_f32_16x16x32_bf16 v[172:175], v[10:13], v[122:125], 0
	v_mfma_f32_16x16x32_bf16 v[98:101], v[2:5], v[122:125], 0
	v_mfma_f32_16x16x32_bf16 v[74:77], v[6:9], v[122:125], 0
	v_mfma_f32_16x16x32_bf16 v[122:125], v[14:17], v[122:125], 0
	s_waitcnt vmcnt(8)
	v_mfma_f32_16x16x32_bf16 v[204:207], v[26:29], v[180:183], v[70:73]
	s_nop 2
	v_lshl_add_u64 v[70:71], v[144:145], 0, v[154:155]
	v_lshl_add_u64 v[72:73], v[144:145], 0, v[156:157]
	global_load_dwordx4 v[154:157], v[220:221], off
	s_waitcnt vmcnt(8)
	v_mfma_f32_16x16x32_bf16 v[150:153], v[26:29], v[192:195], v[172:175]
	global_load_dwordx2 v[220:221], v[84:85], off
	s_nop 1
	global_load_dwordx4 v[172:175], v[222:223], off
	v_mfma_f32_16x16x32_bf16 v[106:109], v[18:21], v[180:183], v[106:109]
	v_mfma_f32_16x16x32_bf16 v[98:101], v[18:21], v[192:195], v[98:101]
	v_mfma_f32_16x16x32_bf16 v[90:93], v[22:25], v[180:183], v[90:93]
	v_mfma_f32_16x16x32_bf16 v[74:77], v[22:25], v[192:195], v[74:77]
	v_mfma_f32_16x16x32_bf16 v[114:117], v[30:33], v[180:183], v[114:117]
	v_mfma_f32_16x16x32_bf16 v[122:125], v[30:33], v[192:195], v[122:125]
	global_load_dwordx2 v[192:193], v[84:85], off offset:32
	global_load_dwordx2 v[194:195], v[84:85], off offset:64
	global_load_dwordx2 v[222:223], v[84:85], off offset:96
	global_load_dwordx4 v[180:183], v[70:71], off
	global_load_dwordx2 v[226:227], v[218:219], off
	s_waitcnt lgkmcnt(7)
	v_mfma_f32_16x16x32_bf16 v[176:179], v[34:37], v[188:191], v[176:179]
	global_load_dwordx4 v[184:187], v[72:73], off
	global_load_dwordx2 v[228:229], v[218:219], off offset:32
	global_load_dwordx2 v[230:231], v[158:159], off
	v_lshl_add_u64 v[70:71], v[148:149], 0, v[130:131]
	s_waitcnt lgkmcnt(6)
	v_mfma_f32_16x16x32_bf16 v[84:87], v[38:41], v[188:191], v[86:89]
	s_waitcnt vmcnt(0)
	v_lshlrev_b32_e32 v245, 16, v231
	s_waitcnt lgkmcnt(5)
	v_mfma_f32_16x16x32_bf16 v[94:97], v[42:45], v[188:191], v[94:97]
	v_lshlrev_b32_e32 v244, 16, v230
	v_and_b32_e32 v231, 0xffff0000, v231
	v_and_b32_e32 v230, 0xffff0000, v230
	s_waitcnt lgkmcnt(4)
	v_mfma_f32_16x16x32_bf16 v[110:113], v[46:49], v[188:191], v[110:113]
	global_load_dwordx4 v[188:191], v[224:225], off
	s_nop 0
	global_load_dwordx2 v[224:225], v[218:219], off offset:64
	v_mfma_f32_16x16x32_bf16 v[106:109], v[34:37], v[196:199], v[106:109]
	global_load_dwordx2 v[218:219], v[218:219], off offset:96
	s_nop 0
	global_load_dwordx2 v[232:233], v[158:159], off offset:32
	global_load_dword v234, v[68:69], off offset:64
	global_load_dword v236, v[68:69], off offset:128
	global_load_dword v238, v[68:69], off offset:192
	global_load_dwordx2 v[240:241], v[158:159], off offset:64
	global_load_dwordx2 v[242:243], v[158:159], off offset:96
	v_mfma_f32_16x16x32_bf16 v[102:105], v[34:37], v[154:157], v[102:105]
	v_lshl_add_u64 v[68:69], v[160:161], 1, v[146:147]
	s_waitcnt vmcnt(5)
	v_lshlrev_b32_e32 v247, 16, v233
	v_mfma_f32_16x16x32_bf16 v[98:101], v[34:37], v[172:175], v[98:101]
	v_lshlrev_b32_e32 v246, 16, v232
	v_and_b32_e32 v233, 0xffff0000, v233
	v_and_b32_e32 v232, 0xffff0000, v232
	v_mfma_f32_16x16x32_bf16 v[88:91], v[38:41], v[196:199], v[90:93]
	s_waitcnt vmcnt(1)
	v_lshlrev_b32_e32 v249, 16, v241
	v_lshlrev_b32_e32 v248, 16, v240
	v_mfma_f32_16x16x32_bf16 v[80:83], v[38:41], v[154:157], v[80:83]
	v_mfma_f32_16x16x32_bf16 v[72:75], v[38:41], v[172:175], v[74:77]
	v_mfma_f32_16x16x32_bf16 v[158:161], v[42:45], v[196:199], v[204:207]
	s_nop 1
	v_lshlrev_b32_e32 v77, 16, v211
	v_lshlrev_b32_e32 v76, 16, v210
	v_mfma_f32_16x16x32_bf16 v[126:129], v[42:45], v[154:157], v[126:129]
	v_and_b32_e32 v205, 0xffff0000, v211
	v_and_b32_e32 v204, 0xffff0000, v210
	v_lshlrev_b32_e32 v207, 16, v213
	v_mfma_f32_16x16x32_bf16 v[150:153], v[42:45], v[172:175], v[150:153]
	v_lshlrev_b32_e32 v206, 16, v212
	v_and_b32_e32 v211, 0xffff0000, v213
	v_and_b32_e32 v210, 0xffff0000, v212
	v_mfma_f32_16x16x32_bf16 v[114:117], v[46:49], v[196:199], v[114:117]
	v_and_b32_e32 v197, 0xffff0000, v215
	v_and_b32_e32 v196, 0xffff0000, v214
	v_lshlrev_b32_e32 v213, 16, v215
	v_mfma_f32_16x16x32_bf16 v[118:121], v[46:49], v[154:157], v[118:121]
	v_lshlrev_b32_e32 v212, 16, v214
	v_and_b32_e32 v215, 0xffff0000, v217
	v_and_b32_e32 v214, 0xffff0000, v216
	v_mfma_f32_16x16x32_bf16 v[122:125], v[46:49], v[172:175], v[122:125]
	v_and_b32_e32 v175, 0xffff0000, v221
	v_and_b32_e32 v174, 0xffff0000, v220
	v_lshlrev_b32_e32 v199, 16, v217
	s_waitcnt lgkmcnt(3)
	v_mfma_f32_16x16x32_bf16 v[154:157], v[50:53], v[200:203], v[176:179]
	v_lshlrev_b32_e32 v198, 16, v216
	v_lshlrev_b32_e32 v173, 16, v221
	v_lshlrev_b32_e32 v172, 16, v220
	s_waitcnt lgkmcnt(2)
	v_mfma_f32_16x16x32_bf16 v[84:87], v[54:57], v[200:203], v[84:87]
	v_lshlrev_b32_e32 v177, 16, v193
	v_lshlrev_b32_e32 v176, 16, v192
	v_and_b32_e32 v179, 0xffff0000, v193
	s_waitcnt lgkmcnt(1)
	v_mfma_f32_16x16x32_bf16 v[92:95], v[58:61], v[200:203], v[94:97]
	v_and_b32_e32 v178, 0xffff0000, v192
	v_lshlrev_b32_e32 v193, 16, v195
	v_lshlrev_b32_e32 v192, 16, v194
	s_waitcnt lgkmcnt(0)
	v_mfma_f32_16x16x32_bf16 v[110:113], v[62:65], v[200:203], v[110:113]
	v_and_b32_e32 v195, 0xffff0000, v195
	v_and_b32_e32 v194, 0xffff0000, v194
	v_lshlrev_b32_e32 v201, 16, v223
	v_mfma_f32_16x16x32_bf16 v[106:109], v[50:53], v[180:183], v[106:109]
	v_lshlrev_b32_e32 v200, 16, v222
	v_and_b32_e32 v203, 0xffff0000, v223
	v_and_b32_e32 v202, 0xffff0000, v222
	v_mfma_f32_16x16x32_bf16 v[102:105], v[50:53], v[184:187], v[102:105]
	v_lshlrev_b32_e32 v217, 16, v227
	v_lshlrev_b32_e32 v216, 16, v226
	v_and_b32_e32 v221, 0xffff0000, v227
	v_mfma_f32_16x16x32_bf16 v[96:99], v[50:53], v[188:191], v[98:101]
	v_and_b32_e32 v220, 0xffff0000, v226
	v_lshlrev_b32_e32 v223, 16, v229
	v_lshlrev_b32_e32 v222, 16, v228
	v_mfma_f32_16x16x32_bf16 v[88:91], v[54:57], v[180:183], v[88:91]
	v_and_b32_e32 v101, 0xffff0000, v229
	v_and_b32_e32 v100, 0xffff0000, v228
	v_lshlrev_b32_e32 v227, 16, v225
	v_mfma_f32_16x16x32_bf16 v[80:83], v[54:57], v[184:187], v[80:83]
	v_lshlrev_b32_e32 v226, 16, v224
	v_and_b32_e32 v225, 0xffff0000, v225
	v_and_b32_e32 v224, 0xffff0000, v224
	v_mfma_f32_16x16x32_bf16 v[72:75], v[54:57], v[188:191], v[72:75]
	v_lshlrev_b32_e32 v229, 16, v219
	v_lshlrev_b32_e32 v228, 16, v218
	v_and_b32_e32 v219, 0xffff0000, v219
	v_mfma_f32_16x16x32_bf16 v[158:161], v[58:61], v[180:183], v[158:161]
	v_and_b32_e32 v218, 0xffff0000, v218
	v_mfma_f32_16x16x32_bf16 v[126:129], v[58:61], v[184:187], v[126:129]
	v_mfma_f32_16x16x32_bf16 v[150:153], v[58:61], v[188:191], v[150:153]
	v_mfma_f32_16x16x32_bf16 v[114:117], v[62:65], v[180:183], v[114:117]
	v_and_b32_e32 v181, 0xffff0000, v241
	v_and_b32_e32 v180, 0xffff0000, v240
	s_waitcnt vmcnt(0)
	v_lshlrev_b32_e32 v183, 16, v243
	v_mfma_f32_16x16x32_bf16 v[118:121], v[62:65], v[184:187], v[118:121]
	v_mov_b32_e32 v186, v154
	v_mov_b32_e32 v187, v156
	v_mov_b32_e32 v156, v155
	v_mfma_f32_16x16x32_bf16 v[122:125], v[62:65], v[188:191], v[122:125]
	v_mov_b32_e32 v155, v86
	v_mov_b32_e32 v86, v85
	v_mov_b32_e32 v85, v94
	v_mov_b32_e32 v94, v93
	v_mov_b32_e32 v154, v84
	v_mov_b32_e32 v84, v92
	v_mov_b32_e32 v92, v110
	v_mov_b32_e32 v93, v112
	v_mov_b32_e32 v112, v111
	v_pk_add_f32 v[110:111], v[208:209], v[186:187] op_sel_hi:[0,1]
	v_pk_add_f32 v[156:157], v[208:209], v[156:157] op_sel_hi:[0,1]
	v_pk_add_f32 v[94:95], v[208:209], v[94:95] op_sel_hi:[0,1]
	v_mov_b32_e32 v187, v108
	v_mov_b32_e32 v108, v107
	v_pk_add_f32 v[154:155], v[208:209], v[154:155] op_sel_hi:[0,1]
	v_pk_add_f32 v[86:87], v[208:209], v[86:87] op_sel_hi:[0,1]
	v_pk_add_f32 v[84:85], v[208:209], v[84:85] op_sel_hi:[0,1]
	v_pk_add_f32 v[112:113], v[208:209], v[112:113] op_sel_hi:[0,1]
	v_mov_b32_e32 v186, v106
	v_mov_b32_e32 v106, v88
	v_mov_b32_e32 v107, v90
	v_mov_b32_e32 v90, v89
	v_mov_b32_e32 v88, v158
	v_mov_b32_e32 v89, v160
	v_mov_b32_e32 v160, v159
	v_mov_b32_e32 v158, v114
	v_mov_b32_e32 v159, v116
	v_mov_b32_e32 v116, v115
	v_mov_b32_e32 v114, v102
	v_mov_b32_e32 v115, v104
	v_mov_b32_e32 v104, v103
	v_mov_b32_e32 v102, v80
	v_mov_b32_e32 v103, v82
	v_mov_b32_e32 v82, v81
	v_mov_b32_e32 v80, v126
	v_mov_b32_e32 v81, v128
	v_mov_b32_e32 v128, v127
	v_mov_b32_e32 v126, v118
	v_mov_b32_e32 v127, v120
	v_mov_b32_e32 v120, v119
	v_mov_b32_e32 v118, v96
	v_mov_b32_e32 v119, v98
	v_mov_b32_e32 v98, v97
	v_mov_b32_e32 v96, v72
	v_mov_b32_e32 v97, v74
	v_mov_b32_e32 v74, v73
	v_mov_b32_e32 v72, v150
	v_mov_b32_e32 v73, v152
	v_mov_b32_e32 v152, v151
	v_pk_mul_f32 v[76:77], v[110:111], v[76:77]
	v_mov_b32_e32 v110, v122
	v_mov_b32_e32 v111, v124
	v_mov_b32_e32 v124, v123
	v_pk_mul_f32 v[122:123], v[156:157], v[204:205]
	v_pk_mul_f32 v[94:95], v[94:95], v[196:197]
	v_pk_add_f32 v[108:109], v[234:235], v[108:109] op_sel_hi:[0,1]
	v_and_b32_e32 v185, 0xffff0000, v243
	v_and_b32_e32 v184, 0xffff0000, v242
	v_pk_add_f32 v[92:93], v[208:209], v[92:93] op_sel_hi:[0,1]
	v_pk_mul_f32 v[150:151], v[154:155], v[206:207]
	v_pk_mul_f32 v[86:87], v[86:87], v[210:211]
	v_pk_mul_f32 v[84:85], v[84:85], v[212:213]
	v_pk_mul_f32 v[112:113], v[112:113], v[214:215]
	v_pk_add_f32 v[154:155], v[234:235], v[186:187] op_sel_hi:[0,1]
	v_pk_add_f32 v[106:107], v[234:235], v[106:107] op_sel_hi:[0,1]
	v_pk_add_f32 v[90:91], v[234:235], v[90:91] op_sel_hi:[0,1]
	v_pk_add_f32 v[156:157], v[234:235], v[160:161] op_sel_hi:[0,1]
	v_pk_add_f32 v[158:159], v[234:235], v[158:159] op_sel_hi:[0,1]
	v_pk_add_f32 v[116:117], v[234:235], v[116:117] op_sel_hi:[0,1]
	v_pk_add_f32 v[104:105], v[236:237], v[104:105] op_sel_hi:[0,1]
	v_pk_add_f32 v[82:83], v[236:237], v[82:83] op_sel_hi:[0,1]
	v_pk_add_f32 v[128:129], v[236:237], v[128:129] op_sel_hi:[0,1]
	v_pk_add_f32 v[120:121], v[236:237], v[120:121] op_sel_hi:[0,1]
	v_pk_add_f32 v[98:99], v[238:239], v[98:99] op_sel_hi:[0,1]
	v_pk_add_f32 v[74:75], v[238:239], v[74:75] op_sel_hi:[0,1]
	v_pk_add_f32 v[72:73], v[238:239], v[72:73] op_sel_hi:[0,1]
	v_pk_add_f32 v[152:153], v[238:239], v[152:153] op_sel_hi:[0,1]
	v_pk_add_f32 v[124:125], v[238:239], v[124:125] op_sel_hi:[0,1]
	v_and_b32_sdwa v160, v76, v170 dst_sel:DWORD dst_unused:UNUSED_PAD src0_sel:WORD_1 src1_sel:DWORD
	v_and_b32_sdwa v161, v123, v170 dst_sel:DWORD dst_unused:UNUSED_PAD src0_sel:WORD_1 src1_sel:DWORD
	v_and_b32_sdwa v171, v122, v170 dst_sel:DWORD dst_unused:UNUSED_PAD src0_sel:WORD_1 src1_sel:DWORD
	v_and_b32_sdwa v196, v95, v170 dst_sel:DWORD dst_unused:UNUSED_PAD src0_sel:WORD_1 src1_sel:DWORD
	v_and_b32_sdwa v197, v94, v170 dst_sel:DWORD dst_unused:UNUSED_PAD src0_sel:WORD_1 src1_sel:DWORD
	v_pk_mul_f32 v[108:109], v[108:109], v[174:175]
	v_lshlrev_b32_e32 v182, 16, v242
	v_pk_mul_f32 v[92:93], v[92:93], v[198:199]
	v_pk_add_f32 v[88:89], v[234:235], v[88:89] op_sel_hi:[0,1]
	v_pk_add_f32 v[114:115], v[236:237], v[114:115] op_sel_hi:[0,1]
	v_pk_add_f32 v[102:103], v[236:237], v[102:103] op_sel_hi:[0,1]
	v_pk_add_f32 v[80:81], v[236:237], v[80:81] op_sel_hi:[0,1]
	v_pk_add_f32 v[126:127], v[236:237], v[126:127] op_sel_hi:[0,1]
	v_pk_add_f32 v[118:119], v[238:239], v[118:119] op_sel_hi:[0,1]
	v_pk_add_f32 v[96:97], v[238:239], v[96:97] op_sel_hi:[0,1]
	v_pk_add_f32 v[110:111], v[238:239], v[110:111] op_sel_hi:[0,1]
	v_and_b32_sdwa v130, v77, v170 dst_sel:DWORD dst_unused:UNUSED_PAD src0_sel:WORD_1 src1_sel:DWORD
	v_and_b32_sdwa v186, v151, v170 dst_sel:DWORD dst_unused:UNUSED_PAD src0_sel:WORD_1 src1_sel:DWORD
	v_and_b32_sdwa v187, v150, v170 dst_sel:DWORD dst_unused:UNUSED_PAD src0_sel:WORD_1 src1_sel:DWORD
	v_and_b32_sdwa v188, v87, v170 dst_sel:DWORD dst_unused:UNUSED_PAD src0_sel:WORD_1 src1_sel:DWORD
	v_and_b32_sdwa v189, v86, v170 dst_sel:DWORD dst_unused:UNUSED_PAD src0_sel:WORD_1 src1_sel:DWORD
	v_and_b32_sdwa v190, v85, v170 dst_sel:DWORD dst_unused:UNUSED_PAD src0_sel:WORD_1 src1_sel:DWORD
	v_and_b32_sdwa v191, v84, v170 dst_sel:DWORD dst_unused:UNUSED_PAD src0_sel:WORD_1 src1_sel:DWORD
	v_and_b32_sdwa v204, v113, v170 dst_sel:DWORD dst_unused:UNUSED_PAD src0_sel:WORD_1 src1_sel:DWORD
	v_and_b32_sdwa v205, v112, v170 dst_sel:DWORD dst_unused:UNUSED_PAD src0_sel:WORD_1 src1_sel:DWORD
	v_pk_mul_f32 v[154:155], v[154:155], v[172:173]
	v_pk_mul_f32 v[106:107], v[106:107], v[176:177]
	v_pk_mul_f32 v[90:91], v[90:91], v[178:179]
	v_pk_mul_f32 v[156:157], v[156:157], v[194:195]
	v_pk_mul_f32 v[158:159], v[158:159], v[200:201]
	v_pk_mul_f32 v[116:117], v[116:117], v[202:203]
	v_pk_mul_f32 v[104:105], v[104:105], v[220:221]
	v_pk_mul_f32 v[82:83], v[82:83], v[100:101]
	v_pk_mul_f32 v[100:101], v[128:129], v[224:225]
	v_pk_mul_f32 v[120:121], v[120:121], v[218:219]
	v_pk_mul_f32 v[98:99], v[98:99], v[230:231]
	v_pk_mul_f32 v[74:75], v[74:75], v[232:233]
	v_pk_mul_f32 v[72:73], v[72:73], v[248:249]
	v_pk_mul_f32 v[128:129], v[152:153], v[180:181]
	v_pk_mul_f32 v[124:125], v[124:125], v[184:185]
	v_add3_u32 v76, v76, v160, s13
	v_add3_u32 v123, v123, v161, s13
	v_add3_u32 v122, v122, v171, s13
	v_add3_u32 v95, v95, v196, s13
	v_add3_u32 v94, v94, v197, s13
	v_and_b32_sdwa v153, v109, v170 dst_sel:DWORD dst_unused:UNUSED_PAD src0_sel:WORD_1 src1_sel:DWORD
	v_and_b32_sdwa v160, v108, v170 dst_sel:DWORD dst_unused:UNUSED_PAD src0_sel:WORD_1 src1_sel:DWORD
	v_and_b32_sdwa v198, v93, v170 dst_sel:DWORD dst_unused:UNUSED_PAD src0_sel:WORD_1 src1_sel:DWORD
	v_and_b32_sdwa v199, v92, v170 dst_sel:DWORD dst_unused:UNUSED_PAD src0_sel:WORD_1 src1_sel:DWORD
	v_pk_mul_f32 v[88:89], v[88:89], v[192:193]
	v_pk_mul_f32 v[114:115], v[114:115], v[216:217]
	v_pk_mul_f32 v[102:103], v[102:103], v[222:223]
	v_pk_mul_f32 v[80:81], v[80:81], v[226:227]
	v_pk_mul_f32 v[126:127], v[126:127], v[228:229]
	v_pk_mul_f32 v[118:119], v[118:119], v[244:245]
	v_pk_mul_f32 v[96:97], v[96:97], v[246:247]
	v_pk_mul_f32 v[110:111], v[110:111], v[182:183]
	v_add3_u32 v77, v77, v130, s13
	v_add3_u32 v130, v150, v187, s13
	v_add3_u32 v150, v151, v186, s13
	v_add3_u32 v87, v87, v188, s13
	v_add3_u32 v86, v86, v189, s13
	v_add3_u32 v84, v84, v191, s13
	v_add3_u32 v85, v85, v190, s13
	v_add3_u32 v113, v113, v204, s13
	v_add3_u32 v112, v112, v205, s13
	v_and_b32_sdwa v151, v155, v170 dst_sel:DWORD dst_unused:UNUSED_PAD src0_sel:WORD_1 src1_sel:DWORD
	v_and_b32_sdwa v152, v154, v170 dst_sel:DWORD dst_unused:UNUSED_PAD src0_sel:WORD_1 src1_sel:DWORD
	v_and_b32_sdwa v161, v107, v170 dst_sel:DWORD dst_unused:UNUSED_PAD src0_sel:WORD_1 src1_sel:DWORD
	v_and_b32_sdwa v171, v106, v170 dst_sel:DWORD dst_unused:UNUSED_PAD src0_sel:WORD_1 src1_sel:DWORD
	v_and_b32_sdwa v172, v91, v170 dst_sel:DWORD dst_unused:UNUSED_PAD src0_sel:WORD_1 src1_sel:DWORD
	v_and_b32_sdwa v173, v90, v170 dst_sel:DWORD dst_unused:UNUSED_PAD src0_sel:WORD_1 src1_sel:DWORD
	v_and_b32_sdwa v176, v157, v170 dst_sel:DWORD dst_unused:UNUSED_PAD src0_sel:WORD_1 src1_sel:DWORD
	v_and_b32_sdwa v177, v156, v170 dst_sel:DWORD dst_unused:UNUSED_PAD src0_sel:WORD_1 src1_sel:DWORD
	v_and_b32_sdwa v178, v159, v170 dst_sel:DWORD dst_unused:UNUSED_PAD src0_sel:WORD_1 src1_sel:DWORD
	v_and_b32_sdwa v180, v117, v170 dst_sel:DWORD dst_unused:UNUSED_PAD src0_sel:WORD_1 src1_sel:DWORD
	v_and_b32_sdwa v181, v116, v170 dst_sel:DWORD dst_unused:UNUSED_PAD src0_sel:WORD_1 src1_sel:DWORD
	v_and_b32_sdwa v184, v105, v170 dst_sel:DWORD dst_unused:UNUSED_PAD src0_sel:WORD_1 src1_sel:DWORD
	v_and_b32_sdwa v185, v104, v170 dst_sel:DWORD dst_unused:UNUSED_PAD src0_sel:WORD_1 src1_sel:DWORD
	v_and_b32_sdwa v188, v83, v170 dst_sel:DWORD dst_unused:UNUSED_PAD src0_sel:WORD_1 src1_sel:DWORD
	v_and_b32_sdwa v189, v82, v170 dst_sel:DWORD dst_unused:UNUSED_PAD src0_sel:WORD_1 src1_sel:DWORD
	v_and_b32_sdwa v192, v101, v170 dst_sel:DWORD dst_unused:UNUSED_PAD src0_sel:WORD_1 src1_sel:DWORD
	v_and_b32_sdwa v193, v100, v170 dst_sel:DWORD dst_unused:UNUSED_PAD src0_sel:WORD_1 src1_sel:DWORD
	v_and_b32_sdwa v196, v121, v170 dst_sel:DWORD dst_unused:UNUSED_PAD src0_sel:WORD_1 src1_sel:DWORD
	v_and_b32_sdwa v197, v120, v170 dst_sel:DWORD dst_unused:UNUSED_PAD src0_sel:WORD_1 src1_sel:DWORD
	v_and_b32_sdwa v200, v99, v170 dst_sel:DWORD dst_unused:UNUSED_PAD src0_sel:WORD_1 src1_sel:DWORD
	v_and_b32_sdwa v201, v98, v170 dst_sel:DWORD dst_unused:UNUSED_PAD src0_sel:WORD_1 src1_sel:DWORD
	v_and_b32_sdwa v204, v75, v170 dst_sel:DWORD dst_unused:UNUSED_PAD src0_sel:WORD_1 src1_sel:DWORD
	v_and_b32_sdwa v205, v74, v170 dst_sel:DWORD dst_unused:UNUSED_PAD src0_sel:WORD_1 src1_sel:DWORD
	v_and_b32_sdwa v206, v73, v170 dst_sel:DWORD dst_unused:UNUSED_PAD src0_sel:WORD_1 src1_sel:DWORD
	v_and_b32_sdwa v207, v72, v170 dst_sel:DWORD dst_unused:UNUSED_PAD src0_sel:WORD_1 src1_sel:DWORD
	v_and_b32_sdwa v208, v129, v170 dst_sel:DWORD dst_unused:UNUSED_PAD src0_sel:WORD_1 src1_sel:DWORD
	v_and_b32_sdwa v209, v128, v170 dst_sel:DWORD dst_unused:UNUSED_PAD src0_sel:WORD_1 src1_sel:DWORD
	v_and_b32_sdwa v212, v125, v170 dst_sel:DWORD dst_unused:UNUSED_PAD src0_sel:WORD_1 src1_sel:DWORD
	v_and_b32_sdwa v213, v124, v170 dst_sel:DWORD dst_unused:UNUSED_PAD src0_sel:WORD_1 src1_sel:DWORD
	v_and_b32_e32 v123, 0xffff0000, v123
	v_and_b32_e32 v122, 0xffff0000, v122
	v_and_b32_e32 v95, 0xffff0000, v95
	v_and_b32_e32 v94, 0xffff0000, v94
	v_add3_u32 v109, v109, v153, s13
	v_add3_u32 v108, v108, v160, s13
	v_add3_u32 v92, v92, v199, s13
	v_add3_u32 v93, v93, v198, s13
	v_and_b32_sdwa v174, v89, v170 dst_sel:DWORD dst_unused:UNUSED_PAD src0_sel:WORD_1 src1_sel:DWORD
	v_and_b32_sdwa v175, v88, v170 dst_sel:DWORD dst_unused:UNUSED_PAD src0_sel:WORD_1 src1_sel:DWORD
	v_and_b32_sdwa v179, v158, v170 dst_sel:DWORD dst_unused:UNUSED_PAD src0_sel:WORD_1 src1_sel:DWORD
	v_and_b32_sdwa v182, v115, v170 dst_sel:DWORD dst_unused:UNUSED_PAD src0_sel:WORD_1 src1_sel:DWORD
	v_and_b32_sdwa v183, v114, v170 dst_sel:DWORD dst_unused:UNUSED_PAD src0_sel:WORD_1 src1_sel:DWORD
	v_and_b32_sdwa v186, v103, v170 dst_sel:DWORD dst_unused:UNUSED_PAD src0_sel:WORD_1 src1_sel:DWORD
	v_and_b32_sdwa v187, v102, v170 dst_sel:DWORD dst_unused:UNUSED_PAD src0_sel:WORD_1 src1_sel:DWORD
	v_and_b32_sdwa v190, v81, v170 dst_sel:DWORD dst_unused:UNUSED_PAD src0_sel:WORD_1 src1_sel:DWORD
	v_and_b32_sdwa v191, v80, v170 dst_sel:DWORD dst_unused:UNUSED_PAD src0_sel:WORD_1 src1_sel:DWORD
	v_and_b32_sdwa v194, v127, v170 dst_sel:DWORD dst_unused:UNUSED_PAD src0_sel:WORD_1 src1_sel:DWORD
	v_and_b32_sdwa v195, v126, v170 dst_sel:DWORD dst_unused:UNUSED_PAD src0_sel:WORD_1 src1_sel:DWORD
	v_and_b32_sdwa v198, v119, v170 dst_sel:DWORD dst_unused:UNUSED_PAD src0_sel:WORD_1 src1_sel:DWORD
	v_and_b32_sdwa v199, v118, v170 dst_sel:DWORD dst_unused:UNUSED_PAD src0_sel:WORD_1 src1_sel:DWORD
	v_and_b32_sdwa v202, v97, v170 dst_sel:DWORD dst_unused:UNUSED_PAD src0_sel:WORD_1 src1_sel:DWORD
	v_and_b32_sdwa v203, v96, v170 dst_sel:DWORD dst_unused:UNUSED_PAD src0_sel:WORD_1 src1_sel:DWORD
	v_and_b32_sdwa v210, v111, v170 dst_sel:DWORD dst_unused:UNUSED_PAD src0_sel:WORD_1 src1_sel:DWORD
	v_and_b32_sdwa v211, v110, v170 dst_sel:DWORD dst_unused:UNUSED_PAD src0_sel:WORD_1 src1_sel:DWORD
	v_and_b32_e32 v87, 0xffff0000, v87
	v_and_b32_e32 v86, 0xffff0000, v86
	v_and_b32_e32 v113, 0xffff0000, v113
	v_and_b32_e32 v112, 0xffff0000, v112
	v_add3_u32 v152, v154, v152, s13
	v_add3_u32 v151, v155, v151, s13
	v_add3_u32 v106, v106, v171, s13
	v_add3_u32 v107, v107, v161, s13
	v_add3_u32 v91, v91, v172, s13
	v_add3_u32 v90, v90, v173, s13
	v_add3_u32 v153, v157, v176, s13
	v_add3_u32 v154, v156, v177, s13
	v_add3_u32 v156, v159, v178, s13
	v_add3_u32 v117, v117, v180, s13
	v_add3_u32 v116, v116, v181, s13
	v_add3_u32 v105, v105, v184, s13
	v_add3_u32 v104, v104, v185, s13
	v_add3_u32 v83, v83, v188, s13
	v_add3_u32 v82, v82, v189, s13
	v_add3_u32 v101, v101, v192, s13
	v_add3_u32 v100, v100, v193, s13
	v_add3_u32 v121, v121, v196, s13
	v_add3_u32 v120, v120, v197, s13
	v_add3_u32 v99, v99, v200, s13
	v_add3_u32 v98, v98, v201, s13
	v_add3_u32 v159, v75, v204, s13
	v_add3_u32 v160, v74, v205, s13
	v_add3_u32 v161, v72, v207, s13
	v_add3_u32 v171, v73, v206, s13
	v_add3_u32 v129, v129, v208, s13
	v_add3_u32 v128, v128, v209, s13
	v_add3_u32 v125, v125, v212, s13
	v_add3_u32 v124, v124, v213, s13
	v_or_b32_sdwa v73, v123, v77 dst_sel:DWORD dst_unused:UNUSED_PAD src0_sel:DWORD src1_sel:WORD_1
	v_or_b32_sdwa v72, v122, v76 dst_sel:DWORD dst_unused:UNUSED_PAD src0_sel:DWORD src1_sel:WORD_1
	v_or_b32_sdwa v77, v95, v85 dst_sel:DWORD dst_unused:UNUSED_PAD src0_sel:DWORD src1_sel:WORD_1
	v_or_b32_sdwa v76, v94, v84 dst_sel:DWORD dst_unused:UNUSED_PAD src0_sel:DWORD src1_sel:WORD_1
	v_and_b32_e32 v84, 0xffff0000, v109
	v_and_b32_e32 v85, 0xffff0000, v108
	v_add3_u32 v88, v88, v175, s13
	v_add3_u32 v89, v89, v174, s13
	v_add3_u32 v155, v158, v179, s13
	v_add3_u32 v114, v114, v183, s13
	v_add3_u32 v115, v115, v182, s13
	v_add3_u32 v102, v102, v187, s13
	v_add3_u32 v103, v103, v186, s13
	v_add3_u32 v157, v80, v191, s13
	v_add3_u32 v158, v81, v190, s13
	v_add3_u32 v126, v126, v195, s13
	v_add3_u32 v127, v127, v194, s13
	v_add3_u32 v118, v118, v199, s13
	v_add3_u32 v119, v119, v198, s13
	v_add3_u32 v96, v96, v203, s13
	v_add3_u32 v97, v97, v202, s13
	v_add3_u32 v110, v110, v211, s13
	v_add3_u32 v111, v111, v210, s13
	v_or_b32_sdwa v75, v87, v150 dst_sel:DWORD dst_unused:UNUSED_PAD src0_sel:DWORD src1_sel:WORD_1
	v_or_b32_sdwa v74, v86, v130 dst_sel:DWORD dst_unused:UNUSED_PAD src0_sel:DWORD src1_sel:WORD_1
	v_or_b32_sdwa v81, v113, v93 dst_sel:DWORD dst_unused:UNUSED_PAD src0_sel:DWORD src1_sel:WORD_1
	v_or_b32_sdwa v80, v112, v92 dst_sel:DWORD dst_unused:UNUSED_PAD src0_sel:DWORD src1_sel:WORD_1
	v_and_b32_e32 v86, 0xffff0000, v91
	v_and_b32_e32 v87, 0xffff0000, v90
	v_and_b32_e32 v90, 0xffff0000, v153
	v_and_b32_e32 v91, 0xffff0000, v154
	v_and_b32_e32 v92, 0xffff0000, v117
	v_and_b32_e32 v93, 0xffff0000, v116
	v_and_b32_e32 v94, 0xffff0000, v105
	v_and_b32_e32 v95, 0xffff0000, v104
	v_and_b32_e32 v83, 0xffff0000, v83
	v_and_b32_e32 v82, 0xffff0000, v82
	v_and_b32_e32 v101, 0xffff0000, v101
	v_and_b32_e32 v100, 0xffff0000, v100
	v_and_b32_e32 v104, 0xffff0000, v121
	v_and_b32_e32 v105, 0xffff0000, v120
	v_and_b32_e32 v99, 0xffff0000, v99
	v_and_b32_e32 v98, 0xffff0000, v98
	v_and_b32_e32 v108, 0xffff0000, v159
	v_and_b32_e32 v109, 0xffff0000, v160
	v_and_b32_e32 v112, 0xffff0000, v129
	v_and_b32_e32 v113, 0xffff0000, v128
	v_and_b32_e32 v116, 0xffff0000, v125
	v_and_b32_e32 v117, 0xffff0000, v124
	global_store_dwordx2 v[70:71], v[72:73], off offset:1024
	global_store_dwordx2 v[70:71], v[74:75], off offset:1056
	global_store_dwordx2 v[70:71], v[76:77], off offset:1088
	global_store_dwordx2 v[70:71], v[80:81], off offset:1120
	v_or_b32_sdwa v71, v84, v151 dst_sel:DWORD dst_unused:UNUSED_PAD src0_sel:DWORD src1_sel:WORD_1
	v_or_b32_sdwa v70, v85, v152 dst_sel:DWORD dst_unused:UNUSED_PAD src0_sel:DWORD src1_sel:WORD_1
	v_or_b32_sdwa v73, v86, v107 dst_sel:DWORD dst_unused:UNUSED_PAD src0_sel:DWORD src1_sel:WORD_1
	v_or_b32_sdwa v72, v87, v106 dst_sel:DWORD dst_unused:UNUSED_PAD src0_sel:DWORD src1_sel:WORD_1
	v_or_b32_sdwa v75, v90, v89 dst_sel:DWORD dst_unused:UNUSED_PAD src0_sel:DWORD src1_sel:WORD_1
	v_or_b32_sdwa v74, v91, v88 dst_sel:DWORD dst_unused:UNUSED_PAD src0_sel:DWORD src1_sel:WORD_1
	v_or_b32_sdwa v77, v92, v156 dst_sel:DWORD dst_unused:UNUSED_PAD src0_sel:DWORD src1_sel:WORD_1
	v_or_b32_sdwa v76, v93, v155 dst_sel:DWORD dst_unused:UNUSED_PAD src0_sel:DWORD src1_sel:WORD_1
	v_or_b32_sdwa v81, v94, v115 dst_sel:DWORD dst_unused:UNUSED_PAD src0_sel:DWORD src1_sel:WORD_1
	v_or_b32_sdwa v80, v95, v114 dst_sel:DWORD dst_unused:UNUSED_PAD src0_sel:DWORD src1_sel:WORD_1
	v_or_b32_sdwa v83, v83, v103 dst_sel:DWORD dst_unused:UNUSED_PAD src0_sel:DWORD src1_sel:WORD_1
	v_or_b32_sdwa v82, v82, v102 dst_sel:DWORD dst_unused:UNUSED_PAD src0_sel:DWORD src1_sel:WORD_1
	v_or_b32_sdwa v85, v101, v158 dst_sel:DWORD dst_unused:UNUSED_PAD src0_sel:DWORD src1_sel:WORD_1
	v_or_b32_sdwa v84, v100, v157 dst_sel:DWORD dst_unused:UNUSED_PAD src0_sel:DWORD src1_sel:WORD_1
	v_or_b32_sdwa v87, v104, v127 dst_sel:DWORD dst_unused:UNUSED_PAD src0_sel:DWORD src1_sel:WORD_1
	v_or_b32_sdwa v86, v105, v126 dst_sel:DWORD dst_unused:UNUSED_PAD src0_sel:DWORD src1_sel:WORD_1
	v_or_b32_sdwa v89, v99, v119 dst_sel:DWORD dst_unused:UNUSED_PAD src0_sel:DWORD src1_sel:WORD_1
	v_or_b32_sdwa v88, v98, v118 dst_sel:DWORD dst_unused:UNUSED_PAD src0_sel:DWORD src1_sel:WORD_1
	v_or_b32_sdwa v91, v108, v97 dst_sel:DWORD dst_unused:UNUSED_PAD src0_sel:DWORD src1_sel:WORD_1
	v_or_b32_sdwa v90, v109, v96 dst_sel:DWORD dst_unused:UNUSED_PAD src0_sel:DWORD src1_sel:WORD_1
	v_or_b32_sdwa v93, v112, v171 dst_sel:DWORD dst_unused:UNUSED_PAD src0_sel:DWORD src1_sel:WORD_1
	v_or_b32_sdwa v92, v113, v161 dst_sel:DWORD dst_unused:UNUSED_PAD src0_sel:DWORD src1_sel:WORD_1
	v_or_b32_sdwa v95, v116, v111 dst_sel:DWORD dst_unused:UNUSED_PAD src0_sel:DWORD src1_sel:WORD_1
	v_or_b32_sdwa v94, v117, v110 dst_sel:DWORD dst_unused:UNUSED_PAD src0_sel:DWORD src1_sel:WORD_1
	global_store_dwordx2 v[78:79], v[70:71], off offset:1024
	global_store_dwordx2 v[78:79], v[72:73], off offset:1056
	global_store_dwordx2 v[78:79], v[74:75], off offset:1088
	global_store_dwordx2 v[78:79], v[76:77], off offset:1120
	global_store_dwordx2 v[66:67], v[80:81], off offset:1024
	global_store_dwordx2 v[66:67], v[82:83], off offset:1056
	global_store_dwordx2 v[66:67], v[84:85], off offset:1088
	global_store_dwordx2 v[66:67], v[86:87], off offset:1120
	global_store_dwordx2 v[68:69], v[88:89], off offset:1024
	global_store_dwordx2 v[68:69], v[90:91], off offset:1056
	global_store_dwordx2 v[68:69], v[92:93], off offset:1088
	global_store_dwordx2 v[68:69], v[94:95], off offset:1120
	s_cbranch_vccnz .LBB0_872
	s_waitcnt lgkmcnt(0)
	s_mov_b64 s[6:7], -1
	s_branch .LBB0_865
